# deferred weight transposes: four units of loads in flight per block instead of two
# speedup vs baseline: 1.0002x; 1.0002x over previous
.Ldt0_nrot:
	s_addk_i32 s52, 0xa08
	s_movk_i32 s9, 0x1c10
	s_cmp_ge_u32 s52, s9
	s_cbranch_scc1 .Ldt0_skip
	s_waitcnt lgkmcnt(0)
	s_barrier
	v_readlane_b32 s54, v254, 54
	v_readlane_b32 s55, v254, 55
	v_readlane_b32 s56, v253, 2
	v_readlane_b32 s57, v253, 3
	v_readlane_b32 s58, v253, 8
	v_readlane_b32 s59, v253, 9
	v_readlane_b32 s60, v253, 10
	v_readlane_b32 s61, v253, 11
	v_readlane_b32 s62, v254, 12
	v_readlane_b32 s63, v254, 13
	v_and_b32_e32 v106, 7, v180
	v_lshrrev_b32_e32 v93, 3, v180
	s_add_u32 s54, s54, 0xa080000
	s_addc_u32 s55, s55, 0
	s_add_u32 s58, s58, 0x5000000
	s_addc_u32 s59, s59, 0
	s_add_u32 s60, s60, 0x40000
	s_addc_u32 s61, s61, 0
	v_lshlrev_b32_e32 v94, 4, v106
	v_bfe_u32 v107, v180, 3, 1
	v_lshlrev_b32_e32 v108, 2, v106
	v_lshl_add_u32 v108, v107, 1, v108
	v_mul_u32_u24_e32 v84, 0x410, v108
	v_lshrrev_b32_e32 v109, 3, v93
	v_xor_b32_e32 v109, v109, v106
	v_lshlrev_b32_e32 v109, 3, v109
	v_and_b32_e32 v110, 6, v93
	v_or_b32_e32 v109, v109, v110
	v_lshl_add_u32 v84, v109, 1, v84
	v_cmp_ne_u32_e64 s[74:75], 0, v107
	v_mov_b32_e32 v104, 0x1000504
	v_mov_b32_e32 v105, 0x3020706
	v_mov_b32_e32 v111, 0x5040100
	v_mov_b32_e32 v112, 0x7060302
	v_cndmask_b32_e64 v104, v104, v111, s[74:75]
	v_cndmask_b32_e64 v105, v105, v112, s[74:75]
	v_lshrrev_b32_e32 v106, 6, v180
	v_and_b32_e32 v107, 63, v180
	v_lshrrev_b32_e32 v108, 2, v106
	v_add_u32_e32 v109, 0, v108
	v_xor_b32_e32 v109, v109, v107
	v_lshlrev_b32_e32 v109, 4, v109
	v_add_u32_e32 v110, 0, v106
	v_mul_u32_u24_e32 v110, 0x410, v110
	v_add_u32_e32 v85, v109, v110
	v_add_u32_e32 v109, 2, v108
	v_xor_b32_e32 v109, v109, v107
	v_lshlrev_b32_e32 v109, 4, v109
	v_add_u32_e32 v110, 8, v106
	v_mul_u32_u24_e32 v110, 0x410, v110
	v_add_u32_e32 v86, v109, v110
	v_add_u32_e32 v109, 4, v108
	v_xor_b32_e32 v109, v109, v107
	v_lshlrev_b32_e32 v109, 4, v109
	v_add_u32_e32 v110, 16, v106
	v_mul_u32_u24_e32 v110, 0x410, v110
	v_add_u32_e32 v87, v109, v110
	v_add_u32_e32 v109, 6, v108
	v_xor_b32_e32 v109, v109, v107
	v_lshlrev_b32_e32 v109, 4, v109
	v_add_u32_e32 v110, 24, v106
	v_mul_u32_u24_e32 v110, 0x410, v110
	v_add_u32_e32 v88, v109, v110
	v_lshlrev_b32_e32 v109, 13, v106
	v_lshl_add_u32 v89, v107, 4, v109
	v_add_u32_e32 v90, 0x10000, v89
	v_add_u32_e32 v91, 0x20000, v89
	v_add_u32_e32 v92, 0x30000, v89
	s_mov_b32 s53, 0
	s_mov_b32 s72, 0
	s_mov_b32 s73, 0
	s_mov_b32 s12, 0
	s_mov_b32 s13, 0
	s_cmpk_ge_u32 s52, 0x1410
	s_cbranch_scc1 .Ldt0_out0
	s_sub_i32 s0, s52, 0xa08
	s_mul_i32 s1, s0, 0xcc3
	s_lshr_b32 s1, s1, 20
	s_mul_i32 s2, s1, 0x141
	s_sub_u32 s2, s0, s2
	s_lshl_b32 s3, s2, 7
	s_mul_i32 s4, s1, 0x1410000
	s_add_u32 s3, s3, s4
	s_add_u32 s64, s54, s3
	s_addc_u32 s65, s55, 0
	s_mov_b32 s7, 0xa080
	s_lshl_b32 s4, s1, 10
	s_cmpk_lt_u32 s2, 0x80
	s_cbranch_scc1 .Ldt0_wlo0
	s_cmpk_eq_u32 s2, 0x80
	s_cbranch_scc1 .Ldt0_wlr0
	s_add_i32 s2, s2, -1

.Ldt0_ud0:
	v_mul_u32_u24_e32 v96, s7, v93
	s_lshl_b32 s6, s7, 6
	v_add_u32_e32 v96, v96, v94
	v_add_u32_e32 v97, s6, v96
	v_add_u32_e32 v98, s6, v97
	v_add_u32_e32 v99, s6, v98
	v_add_u32_e32 v100, s6, v99
	v_add_u32_e32 v101, s6, v100
	v_add_u32_e32 v102, s6, v101
	v_add_u32_e32 v103, s6, v102
	global_load_dwordx4 v[4:7], v96, s[64:65] nt
	global_load_dwordx4 v[8:11], v97, s[64:65] nt
	global_load_dwordx4 v[12:15], v98, s[64:65] nt
	global_load_dwordx4 v[16:19], v99, s[64:65] nt
	global_load_dwordx4 v[20:23], v100, s[64:65] nt
	global_load_dwordx4 v[24:27], v101, s[64:65] nt
	global_load_dwordx4 v[28:31], v102, s[64:65] nt
	global_load_dwordx4 v[32:35], v103, s[64:65] nt
	s_mov_b32 s72, 1
	s_add_u32 s52, s52, s84
	s_cmp_ge_u32 s52, s9
	s_cbranch_scc1 .Ldt0_proc0
	s_cmpk_ge_u32 s52, 0x1410
	s_cbranch_scc1 .Ldt0_out1
	s_sub_i32 s0, s52, 0xa08
	s_mul_i32 s1, s0, 0xcc3
	s_lshr_b32 s1, s1, 20
	s_mul_i32 s2, s1, 0x141
	s_sub_u32 s2, s0, s2
	s_lshl_b32 s3, s2, 7
	s_mul_i32 s4, s1, 0x1410000
	s_add_u32 s3, s3, s4
	s_add_u32 s64, s54, s3
	s_addc_u32 s65, s55, 0
	s_mov_b32 s7, 0xa080
	s_lshl_b32 s4, s1, 10
	s_cmpk_lt_u32 s2, 0x80
	s_cbranch_scc1 .Ldt0_wlo1
	s_cmpk_eq_u32 s2, 0x80
	s_cbranch_scc1 .Ldt0_wlr1
	s_add_i32 s2, s2, -1

.Ldt0_out1:
	s_sub_i32 s0, s52, 0x1410
	s_lshr_b32 s1, s0, 10
	s_bfe_u32 s2, s0, 0x30007
	s_and_b32 s3, s0, 0x7f
	s_lshl_b32 s4, s1, 26
	s_lshl_b32 s5, s3, 7
	s_add_u32 s4, s4, s5
	s_lshl_b32 s5, s2, 23
	s_add_u32 s4, s4, s5
	s_add_u32 s64, s56, s4
	s_addc_u32 s65, s57, 0
	s_lshl_b32 s4, s1, 25
	s_lshl_b32 s5, s3, 18
	s_add_u32 s4, s4, s5
	s_lshl_b32 s5, s2, 10
	s_add_u32 s4, s4, s5
	s_add_u32 s10, s62, s4
	s_addc_u32 s11, s63, 0
	s_movk_i32 s7, 0x4000
.Ldt0_ud1:
	v_mul_u32_u24_e32 v96, s7, v93
	s_lshl_b32 s6, s7, 6
	v_add_u32_e32 v96, v96, v94
	v_add_u32_e32 v97, s6, v96
	v_add_u32_e32 v98, s6, v97
	v_add_u32_e32 v99, s6, v98
	v_add_u32_e32 v100, s6, v99
	v_add_u32_e32 v101, s6, v100
	v_add_u32_e32 v102, s6, v101
	v_add_u32_e32 v103, s6, v102
	global_load_dwordx4 v[36:39], v96, s[64:65] nt
	global_load_dwordx4 v[40:43], v97, s[64:65] nt
	global_load_dwordx4 v[44:47], v98, s[64:65] nt
	global_load_dwordx4 v[48:51], v99, s[64:65] nt
	global_load_dwordx4 v[52:55], v100, s[64:65] nt
	global_load_dwordx4 v[56:59], v101, s[64:65] nt
	global_load_dwordx4 v[60:63], v102, s[64:65] nt
	global_load_dwordx4 v[64:67], v103, s[64:65] nt
	s_mov_b32 s73, 1
	s_add_u32 s52, s52, s84
	s_cmp_ge_u32 s52, s9
	s_cbranch_scc1 .Ldt0_proc0
	s_cmpk_ge_u32 s52, 0x1410
	s_cbranch_scc1 .Ldt0_out2
	s_sub_i32 s0, s52, 0xa08
	s_mul_i32 s1, s0, 0xcc3
	s_lshr_b32 s1, s1, 20
	s_mul_i32 s2, s1, 0x141
	s_sub_u32 s2, s0, s2
	s_lshl_b32 s3, s2, 7
	s_mul_i32 s4, s1, 0x1410000
	s_add_u32 s3, s3, s4
	s_add_u32 s64, s54, s3
	s_addc_u32 s65, s55, 0
	s_mov_b32 s7, 0xa080
	s_lshl_b32 s4, s1, 10
	s_cmpk_lt_u32 s2, 0x80
	s_cbranch_scc1 .Ldt0_wlo2
	s_cmpk_eq_u32 s2, 0x80
	s_cbranch_scc1 .Ldt0_wlr2
	s_add_i32 s2, s2, -1
.Ldt0_wlo2:
	s_lshl_b32 s5, s2, 18
	s_add_u32 s5, s5, s4
	s_add_u32 s14, s58, s5
	s_addc_u32 s15, s59, 0
	s_branch .Ldt0_ud2
.Ldt0_wlr2:
	s_add_u32 s14, s60, s4
	s_addc_u32 s15, s61, 0
	s_branch .Ldt0_ud2
.Ldt0_out2:
	s_sub_i32 s0, s52, 0x1410
	s_lshr_b32 s1, s0, 10
	s_bfe_u32 s2, s0, 0x30007
	s_and_b32 s3, s0, 0x7f
	s_lshl_b32 s4, s1, 26
	s_lshl_b32 s5, s3, 7
	s_add_u32 s4, s4, s5
	s_lshl_b32 s5, s2, 23
	s_add_u32 s4, s4, s5
	s_add_u32 s64, s56, s4
	s_addc_u32 s65, s57, 0
	s_lshl_b32 s4, s1, 25
	s_lshl_b32 s5, s3, 18
	s_add_u32 s4, s4, s5
	s_lshl_b32 s5, s2, 10
	s_add_u32 s4, s4, s5
	s_add_u32 s14, s62, s4
	s_addc_u32 s15, s63, 0
	s_movk_i32 s7, 0x4000
.Ldt0_ud2:
	v_mul_u32_u24_e32 v96, s7, v93
	s_lshl_b32 s6, s7, 6
	v_add_u32_e32 v96, v96, v94
	v_add_u32_e32 v97, s6, v96
	v_add_u32_e32 v98, s6, v97
	v_add_u32_e32 v99, s6, v98
	v_add_u32_e32 v100, s6, v99
	v_add_u32_e32 v101, s6, v100
	v_add_u32_e32 v102, s6, v101
	v_add_u32_e32 v103, s6, v102
	global_load_dwordx4 v[130:133], v96, s[64:65] nt
	global_load_dwordx4 v[134:137], v97, s[64:65] nt
	global_load_dwordx4 v[138:141], v98, s[64:65] nt
	global_load_dwordx4 v[142:145], v99, s[64:65] nt
	global_load_dwordx4 v[146:149], v100, s[64:65] nt
	global_load_dwordx4 v[150:153], v101, s[64:65] nt
	global_load_dwordx4 v[154:157], v102, s[64:65] nt
	global_load_dwordx4 v[158:161], v103, s[64:65] nt
	s_mov_b32 s12, 1
	s_add_u32 s52, s52, s84
	s_cmp_ge_u32 s52, s9
	s_cbranch_scc1 .Ldt0_proc0
	s_cmpk_ge_u32 s52, 0x1410
	s_cbranch_scc1 .Ldt0_out3
	s_sub_i32 s0, s52, 0xa08
	s_mul_i32 s1, s0, 0xcc3
	s_lshr_b32 s1, s1, 20
	s_mul_i32 s2, s1, 0x141
	s_sub_u32 s2, s0, s2
	s_lshl_b32 s3, s2, 7
	s_mul_i32 s4, s1, 0x1410000
	s_add_u32 s3, s3, s4
	s_add_u32 s64, s54, s3
	s_addc_u32 s65, s55, 0
	s_mov_b32 s7, 0xa080
	s_lshl_b32 s4, s1, 10
	s_cmpk_lt_u32 s2, 0x80
	s_cbranch_scc1 .Ldt0_wlo3
	s_cmpk_eq_u32 s2, 0x80
	s_cbranch_scc1 .Ldt0_wlr3
	s_add_i32 s2, s2, -1
.Ldt0_wlo3:
	s_lshl_b32 s5, s2, 18
	s_add_u32 s5, s5, s4
	s_add_u32 s90, s58, s5
	s_addc_u32 s91, s59, 0
	s_branch .Ldt0_ud3
.Ldt0_wlr3:
	s_add_u32 s90, s60, s4
	s_addc_u32 s91, s61, 0
	s_branch .Ldt0_ud3
.Ldt0_out3:
	s_sub_i32 s0, s52, 0x1410
	s_lshr_b32 s1, s0, 10
	s_bfe_u32 s2, s0, 0x30007
	s_and_b32 s3, s0, 0x7f
	s_lshl_b32 s4, s1, 26
	s_lshl_b32 s5, s3, 7
	s_add_u32 s4, s4, s5
	s_lshl_b32 s5, s2, 23
	s_add_u32 s4, s4, s5
	s_add_u32 s64, s56, s4
	s_addc_u32 s65, s57, 0
	s_lshl_b32 s4, s1, 25
	s_lshl_b32 s5, s3, 18
	s_add_u32 s4, s4, s5
	s_lshl_b32 s5, s2, 10
	s_add_u32 s4, s4, s5
	s_add_u32 s90, s62, s4
	s_addc_u32 s91, s63, 0
	s_movk_i32 s7, 0x4000
.Ldt0_ud3:
	v_mul_u32_u24_e32 v96, s7, v93
	s_lshl_b32 s6, s7, 6
	v_add_u32_e32 v96, v96, v94
	v_add_u32_e32 v97, s6, v96
	v_add_u32_e32 v98, s6, v97
	v_add_u32_e32 v99, s6, v98
	v_add_u32_e32 v100, s6, v99
	v_add_u32_e32 v101, s6, v100
	v_add_u32_e32 v102, s6, v101
	v_add_u32_e32 v103, s6, v102
	global_load_dwordx4 v[182:185], v96, s[64:65] nt
	global_load_dwordx4 v[186:189], v97, s[64:65] nt
	global_load_dwordx4 v[190:193], v98, s[64:65] nt
	global_load_dwordx4 v[194:197], v99, s[64:65] nt
	global_load_dwordx4 v[198:201], v100, s[64:65] nt
	global_load_dwordx4 v[202:205], v101, s[64:65] nt
	global_load_dwordx4 v[206:209], v102, s[64:65] nt
	global_load_dwordx4 v[210:213], v103, s[64:65] nt
	s_mov_b32 s13, 1
	s_add_u32 s52, s52, s84
.Ldt0_proc0:
	s_add_u32 s0, s73, s12
	s_add_u32 s0, s0, s13
	s_cmp_eq_u32 s0, 3
	s_cbranch_scc0 .Ldt0_wt0
	s_cmp_eq_u32 s53, 0
	s_cbranch_scc1 .Ldt0_ws0_0
	s_cmp_eq_u32 s53, 1
	s_cbranch_scc1 .Ldt0_ws0_1
	s_cmp_eq_u32 s53, 2
	s_cbranch_scc1 .Ldt0_ws0_2
	s_waitcnt vmcnt(36)
	s_branch .Ldt0_wd0
.Ldt0_ws0_0:
	s_waitcnt vmcnt(24)
	s_branch .Ldt0_wd0
.Ldt0_ws0_1:
	s_waitcnt vmcnt(28)
	s_branch .Ldt0_wd0
.Ldt0_ws0_2:
	s_waitcnt vmcnt(32)
	s_branch .Ldt0_wd0
.Ldt0_wt0:
	s_cmp_eq_u32 s0, 2
	s_cbranch_scc0 .Ldt0_wt0_2
	s_waitcnt vmcnt(16)
	s_branch .Ldt0_wd0
.Ldt0_wt0_2:
	s_cmp_eq_u32 s0, 1
	s_cbranch_scc0 .Ldt0_wt0_1
	s_waitcnt vmcnt(8)
	s_branch .Ldt0_wd0

.Ldt0_proc1:
	s_add_u32 s0, s12, s13
	s_add_u32 s0, s0, s72
	s_cmp_eq_u32 s0, 3
	s_cbranch_scc0 .Ldt0_wt1
	s_cmp_eq_u32 s53, 0
	s_cbranch_scc1 .Ldt0_ws1_0
	s_cmp_eq_u32 s53, 1
	s_cbranch_scc1 .Ldt0_ws1_1
	s_cmp_eq_u32 s53, 2
	s_cbranch_scc1 .Ldt0_ws1_2
	s_waitcnt vmcnt(36)
	s_branch .Ldt0_wd1

.Ldt0_wd1:
	v_cvt_pk_bf16_f32 v36, v36, v37
	v_cvt_pk_bf16_f32 v38, v38, v39
	v_cvt_pk_bf16_f32 v40, v40, v41
	v_cvt_pk_bf16_f32 v42, v42, v43
	v_cvt_pk_bf16_f32 v44, v44, v45
	v_cvt_pk_bf16_f32 v46, v46, v47
	v_cvt_pk_bf16_f32 v48, v48, v49
	v_cvt_pk_bf16_f32 v50, v50, v51
	v_cvt_pk_bf16_f32 v52, v52, v53
	v_cvt_pk_bf16_f32 v54, v54, v55
	v_cvt_pk_bf16_f32 v56, v56, v57
	v_cvt_pk_bf16_f32 v58, v58, v59
	v_cvt_pk_bf16_f32 v60, v60, v61
	v_cvt_pk_bf16_f32 v62, v62, v63
	v_cvt_pk_bf16_f32 v64, v64, v65
	v_cvt_pk_bf16_f32 v66, v66, v67
	v_cndmask_b32_e64 v37, v38, v36, s[74:75]
	v_cndmask_b32_e64 v39, v36, v38, s[74:75]
	v_cndmask_b32_e64 v41, v42, v40, s[74:75]
	v_cndmask_b32_e64 v43, v40, v42, s[74:75]
	v_cndmask_b32_e64 v45, v46, v44, s[74:75]
	v_cndmask_b32_e64 v47, v44, v46, s[74:75]
	v_cndmask_b32_e64 v49, v50, v48, s[74:75]
	v_cndmask_b32_e64 v51, v48, v50, s[74:75]
	v_cndmask_b32_e64 v53, v54, v52, s[74:75]
	v_cndmask_b32_e64 v55, v52, v54, s[74:75]
	v_cndmask_b32_e64 v57, v58, v56, s[74:75]
	v_cndmask_b32_e64 v59, v56, v58, s[74:75]
	v_cndmask_b32_e64 v61, v62, v60, s[74:75]
	v_cndmask_b32_e64 v63, v60, v62, s[74:75]
	v_cndmask_b32_e64 v65, v66, v64, s[74:75]
	v_cndmask_b32_e64 v67, v64, v66, s[74:75]
	v_mov_b32_dpp v36, v37 row_ror:8 row_mask:0xf bank_mask:0xf
	v_mov_b32_dpp v40, v41 row_ror:8 row_mask:0xf bank_mask:0xf
	v_mov_b32_dpp v44, v45 row_ror:8 row_mask:0xf bank_mask:0xf
	v_mov_b32_dpp v48, v49 row_ror:8 row_mask:0xf bank_mask:0xf
	v_mov_b32_dpp v52, v53 row_ror:8 row_mask:0xf bank_mask:0xf
	v_mov_b32_dpp v56, v57 row_ror:8 row_mask:0xf bank_mask:0xf
	v_mov_b32_dpp v60, v61 row_ror:8 row_mask:0xf bank_mask:0xf
	v_mov_b32_dpp v64, v65 row_ror:8 row_mask:0xf bank_mask:0xf
	s_nop 1
	v_perm_b32 v68, v39, v36, v104
	v_perm_b32 v69, v39, v36, v105
	v_perm_b32 v70, v43, v40, v104
	v_perm_b32 v71, v43, v40, v105
	v_perm_b32 v72, v47, v44, v104
	v_perm_b32 v73, v47, v44, v105
	v_perm_b32 v74, v51, v48, v104
	v_perm_b32 v75, v51, v48, v105
	v_perm_b32 v76, v55, v52, v104
	v_perm_b32 v77, v55, v52, v105
	v_perm_b32 v78, v59, v56, v104
	v_perm_b32 v79, v59, v56, v105
	v_perm_b32 v80, v63, v60, v104
	v_perm_b32 v81, v63, v60, v105
	v_perm_b32 v82, v67, v64, v104
	v_perm_b32 v83, v67, v64, v105
	s_mov_b64 s[70:71], s[10:11]
	s_mov_b32 s73, 0
	s_cmp_ge_u32 s52, s9
	s_cbranch_scc1 .Ldt0_nl1
	s_cmpk_ge_u32 s52, 0x1410
	s_cbranch_scc1 .Ldt0_out5
	s_sub_i32 s0, s52, 0xa08
	s_mul_i32 s1, s0, 0xcc3
	s_lshr_b32 s1, s1, 20
	s_mul_i32 s2, s1, 0x141
	s_sub_u32 s2, s0, s2
	s_lshl_b32 s3, s2, 7
	s_mul_i32 s4, s1, 0x1410000
	s_add_u32 s3, s3, s4
	s_add_u32 s64, s54, s3
	s_addc_u32 s65, s55, 0
	s_mov_b32 s7, 0xa080
	s_lshl_b32 s4, s1, 10
	s_cmpk_lt_u32 s2, 0x80
	s_cbranch_scc1 .Ldt0_wlo5
	s_cmpk_eq_u32 s2, 0x80
	s_cbranch_scc1 .Ldt0_wlr5
	s_add_i32 s2, s2, -1

.Ldt0_ud5:
	v_mul_u32_u24_e32 v96, s7, v93
	s_lshl_b32 s6, s7, 6
	v_add_u32_e32 v96, v96, v94
	v_add_u32_e32 v97, s6, v96
	v_add_u32_e32 v98, s6, v97
	v_add_u32_e32 v99, s6, v98
	v_add_u32_e32 v100, s6, v99
	v_add_u32_e32 v101, s6, v100
	v_add_u32_e32 v102, s6, v101
	v_add_u32_e32 v103, s6, v102
	global_load_dwordx4 v[36:39], v96, s[64:65] nt
	global_load_dwordx4 v[40:43], v97, s[64:65] nt
	global_load_dwordx4 v[44:47], v98, s[64:65] nt
	global_load_dwordx4 v[48:51], v99, s[64:65] nt
	global_load_dwordx4 v[52:55], v100, s[64:65] nt
	global_load_dwordx4 v[56:59], v101, s[64:65] nt
	global_load_dwordx4 v[60:63], v102, s[64:65] nt
	global_load_dwordx4 v[64:67], v103, s[64:65] nt
	s_mov_b32 s73, 1
	s_add_u32 s52, s52, s84
.Ldt0_nl1:
	ds_write_b32 v84, v68 offset:33280
	ds_write_b32 v84, v69 offset:34320
	ds_write_b32 v84, v70 offset:33408
	ds_write_b32 v84, v71 offset:34448
	ds_write_b32 v84, v72 offset:33536
	ds_write_b32 v84, v73 offset:34576
	ds_write_b32 v84, v74 offset:33664
	ds_write_b32 v84, v75 offset:34704
	ds_write_b32 v84, v76 offset:33792
	ds_write_b32 v84, v77 offset:34832
	ds_write_b32 v84, v78 offset:33920
	ds_write_b32 v84, v79 offset:34960
	ds_write_b32 v84, v80 offset:34048
	ds_write_b32 v84, v81 offset:35088
	ds_write_b32 v84, v82 offset:34176
	ds_write_b32 v84, v83 offset:35216
	s_waitcnt lgkmcnt(0)
	s_barrier
	ds_read_b128 v[68:71], v85 offset:33280
	ds_read_b128 v[72:75], v86 offset:33280
	ds_read_b128 v[76:79], v87 offset:33280
	ds_read_b128 v[80:83], v88 offset:33280
	s_waitcnt lgkmcnt(3)
	global_store_dwordx4 v89, v[68:71], s[70:71] nt
	s_waitcnt lgkmcnt(2)
	global_store_dwordx4 v90, v[72:75], s[70:71] nt
	s_waitcnt lgkmcnt(1)
	global_store_dwordx4 v91, v[76:79], s[70:71] nt
	s_waitcnt lgkmcnt(0)
	global_store_dwordx4 v92, v[80:83], s[70:71] nt
	s_add_u32 s53, s53, 1
	s_cmp_eq_u32 s12, 0
	s_cbranch_scc1 .Ldt0_end
.Ldt0_proc2:
	s_add_u32 s0, s13, s72
	s_add_u32 s0, s0, s73
	s_cmp_eq_u32 s0, 3
	s_cbranch_scc0 .Ldt0_wt2
	s_cmp_eq_u32 s53, 0
	s_cbranch_scc1 .Ldt0_ws2_0
	s_cmp_eq_u32 s53, 1
	s_cbranch_scc1 .Ldt0_ws2_1
	s_cmp_eq_u32 s53, 2
	s_cbranch_scc1 .Ldt0_ws2_2
	s_waitcnt vmcnt(36)
	s_branch .Ldt0_wd2

.Ldt0_wd2:
	v_cvt_pk_bf16_f32 v130, v130, v131
	v_cvt_pk_bf16_f32 v132, v132, v133
	v_cvt_pk_bf16_f32 v134, v134, v135
	v_cvt_pk_bf16_f32 v136, v136, v137
	v_cvt_pk_bf16_f32 v138, v138, v139
	v_cvt_pk_bf16_f32 v140, v140, v141
	v_cvt_pk_bf16_f32 v142, v142, v143
	v_cvt_pk_bf16_f32 v144, v144, v145
	v_cvt_pk_bf16_f32 v146, v146, v147
	v_cvt_pk_bf16_f32 v148, v148, v149
	v_cvt_pk_bf16_f32 v150, v150, v151
	v_cvt_pk_bf16_f32 v152, v152, v153
	v_cvt_pk_bf16_f32 v154, v154, v155
	v_cvt_pk_bf16_f32 v156, v156, v157
	v_cvt_pk_bf16_f32 v158, v158, v159
	v_cvt_pk_bf16_f32 v160, v160, v161
	v_cndmask_b32_e64 v131, v132, v130, s[74:75]
	v_cndmask_b32_e64 v133, v130, v132, s[74:75]
	v_cndmask_b32_e64 v135, v136, v134, s[74:75]
	v_cndmask_b32_e64 v137, v134, v136, s[74:75]
	v_cndmask_b32_e64 v139, v140, v138, s[74:75]
	v_cndmask_b32_e64 v141, v138, v140, s[74:75]
	v_cndmask_b32_e64 v143, v144, v142, s[74:75]
	v_cndmask_b32_e64 v145, v142, v144, s[74:75]
	v_cndmask_b32_e64 v147, v148, v146, s[74:75]
	v_cndmask_b32_e64 v149, v146, v148, s[74:75]
	v_cndmask_b32_e64 v151, v152, v150, s[74:75]
	v_cndmask_b32_e64 v153, v150, v152, s[74:75]
	v_cndmask_b32_e64 v155, v156, v154, s[74:75]
	v_cndmask_b32_e64 v157, v154, v156, s[74:75]
	v_cndmask_b32_e64 v159, v160, v158, s[74:75]
	v_cndmask_b32_e64 v161, v158, v160, s[74:75]
	v_mov_b32_dpp v130, v131 row_ror:8 row_mask:0xf bank_mask:0xf
	v_mov_b32_dpp v134, v135 row_ror:8 row_mask:0xf bank_mask:0xf
	v_mov_b32_dpp v138, v139 row_ror:8 row_mask:0xf bank_mask:0xf
	v_mov_b32_dpp v142, v143 row_ror:8 row_mask:0xf bank_mask:0xf
	v_mov_b32_dpp v146, v147 row_ror:8 row_mask:0xf bank_mask:0xf
	v_mov_b32_dpp v150, v151 row_ror:8 row_mask:0xf bank_mask:0xf
	v_mov_b32_dpp v154, v155 row_ror:8 row_mask:0xf bank_mask:0xf
	v_mov_b32_dpp v158, v159 row_ror:8 row_mask:0xf bank_mask:0xf
	s_nop 1
	v_perm_b32 v68, v133, v130, v104
	v_perm_b32 v69, v133, v130, v105
	v_perm_b32 v70, v137, v134, v104
	v_perm_b32 v71, v137, v134, v105
	v_perm_b32 v72, v141, v138, v104
	v_perm_b32 v73, v141, v138, v105
	v_perm_b32 v74, v145, v142, v104
	v_perm_b32 v75, v145, v142, v105
	v_perm_b32 v76, v149, v146, v104
	v_perm_b32 v77, v149, v146, v105
	v_perm_b32 v78, v153, v150, v104
	v_perm_b32 v79, v153, v150, v105
	v_perm_b32 v80, v157, v154, v104
	v_perm_b32 v81, v157, v154, v105
	v_perm_b32 v82, v161, v158, v104
	v_perm_b32 v83, v161, v158, v105
	s_mov_b64 s[70:71], s[14:15]
	s_mov_b32 s12, 0
	s_cmp_ge_u32 s52, s9
	s_cbranch_scc1 .Ldt0_nl2
	s_cmpk_ge_u32 s52, 0x1410
	s_cbranch_scc1 .Ldt0_out6
	s_sub_i32 s0, s52, 0xa08
	s_mul_i32 s1, s0, 0xcc3
	s_lshr_b32 s1, s1, 20
	s_mul_i32 s2, s1, 0x141
	s_sub_u32 s2, s0, s2
	s_lshl_b32 s3, s2, 7
	s_mul_i32 s4, s1, 0x1410000
	s_add_u32 s3, s3, s4
	s_add_u32 s64, s54, s3
	s_addc_u32 s65, s55, 0
	s_mov_b32 s7, 0xa080
	s_lshl_b32 s4, s1, 10
	s_cmpk_lt_u32 s2, 0x80
	s_cbranch_scc1 .Ldt0_wlo6
	s_cmpk_eq_u32 s2, 0x80
	s_cbranch_scc1 .Ldt0_wlr6
	s_add_i32 s2, s2, -1

.Ldt0_ud6:
	v_mul_u32_u24_e32 v96, s7, v93
	s_lshl_b32 s6, s7, 6
	v_add_u32_e32 v96, v96, v94
	v_add_u32_e32 v97, s6, v96
	v_add_u32_e32 v98, s6, v97
	v_add_u32_e32 v99, s6, v98
	v_add_u32_e32 v100, s6, v99
	v_add_u32_e32 v101, s6, v100
	v_add_u32_e32 v102, s6, v101
	v_add_u32_e32 v103, s6, v102
	global_load_dwordx4 v[130:133], v96, s[64:65] nt
	global_load_dwordx4 v[134:137], v97, s[64:65] nt
	global_load_dwordx4 v[138:141], v98, s[64:65] nt
	global_load_dwordx4 v[142:145], v99, s[64:65] nt
	global_load_dwordx4 v[146:149], v100, s[64:65] nt
	global_load_dwordx4 v[150:153], v101, s[64:65] nt
	global_load_dwordx4 v[154:157], v102, s[64:65] nt
	global_load_dwordx4 v[158:161], v103, s[64:65] nt
	s_mov_b32 s12, 1
	s_add_u32 s52, s52, s84
.Ldt0_nl2:
	ds_write_b32 v84, v68 offset:0
	ds_write_b32 v84, v69 offset:1040
	ds_write_b32 v84, v70 offset:128
	ds_write_b32 v84, v71 offset:1168
	ds_write_b32 v84, v72 offset:256
	ds_write_b32 v84, v73 offset:1296
	ds_write_b32 v84, v74 offset:384
	ds_write_b32 v84, v75 offset:1424
	ds_write_b32 v84, v76 offset:512
	ds_write_b32 v84, v77 offset:1552
	ds_write_b32 v84, v78 offset:640
	ds_write_b32 v84, v79 offset:1680
	ds_write_b32 v84, v80 offset:768
	ds_write_b32 v84, v81 offset:1808
	ds_write_b32 v84, v82 offset:896
	ds_write_b32 v84, v83 offset:1936
	s_waitcnt lgkmcnt(0)
	s_barrier
	ds_read_b128 v[68:71], v85 offset:0
	ds_read_b128 v[72:75], v86 offset:0
	ds_read_b128 v[76:79], v87 offset:0
	ds_read_b128 v[80:83], v88 offset:0
	s_waitcnt lgkmcnt(3)
	global_store_dwordx4 v89, v[68:71], s[70:71] nt
	s_waitcnt lgkmcnt(2)
	global_store_dwordx4 v90, v[72:75], s[70:71] nt
	s_waitcnt lgkmcnt(1)
	global_store_dwordx4 v91, v[76:79], s[70:71] nt
	s_waitcnt lgkmcnt(0)
	global_store_dwordx4 v92, v[80:83], s[70:71] nt
	s_add_u32 s53, s53, 1
	s_cmp_eq_u32 s13, 0
	s_cbranch_scc1 .Ldt0_end
.Ldt0_proc3:
	s_add_u32 s0, s72, s73
	s_add_u32 s0, s0, s12
	s_cmp_eq_u32 s0, 3
	s_cbranch_scc0 .Ldt0_wt3
	s_cmp_eq_u32 s53, 0
	s_cbranch_scc1 .Ldt0_ws3_0
	s_cmp_eq_u32 s53, 1
	s_cbranch_scc1 .Ldt0_ws3_1
	s_cmp_eq_u32 s53, 2
	s_cbranch_scc1 .Ldt0_ws3_2
	s_waitcnt vmcnt(36)
	s_branch .Ldt0_wd3

.Ldt0_wd3:
	v_cvt_pk_bf16_f32 v182, v182, v183
	v_cvt_pk_bf16_f32 v184, v184, v185
	v_cvt_pk_bf16_f32 v186, v186, v187
	v_cvt_pk_bf16_f32 v188, v188, v189
	v_cvt_pk_bf16_f32 v190, v190, v191
	v_cvt_pk_bf16_f32 v192, v192, v193
	v_cvt_pk_bf16_f32 v194, v194, v195
	v_cvt_pk_bf16_f32 v196, v196, v197
	v_cvt_pk_bf16_f32 v198, v198, v199
	v_cvt_pk_bf16_f32 v200, v200, v201
	v_cvt_pk_bf16_f32 v202, v202, v203
	v_cvt_pk_bf16_f32 v204, v204, v205
	v_cvt_pk_bf16_f32 v206, v206, v207
	v_cvt_pk_bf16_f32 v208, v208, v209
	v_cvt_pk_bf16_f32 v210, v210, v211
	v_cvt_pk_bf16_f32 v212, v212, v213
	v_cndmask_b32_e64 v183, v184, v182, s[74:75]
	v_cndmask_b32_e64 v185, v182, v184, s[74:75]
	v_cndmask_b32_e64 v187, v188, v186, s[74:75]
	v_cndmask_b32_e64 v189, v186, v188, s[74:75]
	v_cndmask_b32_e64 v191, v192, v190, s[74:75]
	v_cndmask_b32_e64 v193, v190, v192, s[74:75]
	v_cndmask_b32_e64 v195, v196, v194, s[74:75]
	v_cndmask_b32_e64 v197, v194, v196, s[74:75]
	v_cndmask_b32_e64 v199, v200, v198, s[74:75]
	v_cndmask_b32_e64 v201, v198, v200, s[74:75]
	v_cndmask_b32_e64 v203, v204, v202, s[74:75]
	v_cndmask_b32_e64 v205, v202, v204, s[74:75]
	v_cndmask_b32_e64 v207, v208, v206, s[74:75]
	v_cndmask_b32_e64 v209, v206, v208, s[74:75]
	v_cndmask_b32_e64 v211, v212, v210, s[74:75]
	v_cndmask_b32_e64 v213, v210, v212, s[74:75]
	v_mov_b32_dpp v182, v183 row_ror:8 row_mask:0xf bank_mask:0xf
	v_mov_b32_dpp v186, v187 row_ror:8 row_mask:0xf bank_mask:0xf
	v_mov_b32_dpp v190, v191 row_ror:8 row_mask:0xf bank_mask:0xf
	v_mov_b32_dpp v194, v195 row_ror:8 row_mask:0xf bank_mask:0xf
	v_mov_b32_dpp v198, v199 row_ror:8 row_mask:0xf bank_mask:0xf
	v_mov_b32_dpp v202, v203 row_ror:8 row_mask:0xf bank_mask:0xf
	v_mov_b32_dpp v206, v207 row_ror:8 row_mask:0xf bank_mask:0xf
	v_mov_b32_dpp v210, v211 row_ror:8 row_mask:0xf bank_mask:0xf
	s_nop 1
	v_perm_b32 v68, v185, v182, v104
	v_perm_b32 v69, v185, v182, v105
	v_perm_b32 v70, v189, v186, v104
	v_perm_b32 v71, v189, v186, v105
	v_perm_b32 v72, v193, v190, v104
	v_perm_b32 v73, v193, v190, v105
	v_perm_b32 v74, v197, v194, v104
	v_perm_b32 v75, v197, v194, v105
	v_perm_b32 v76, v201, v198, v104
	v_perm_b32 v77, v201, v198, v105
	v_perm_b32 v78, v205, v202, v104
	v_perm_b32 v79, v205, v202, v105
	v_perm_b32 v80, v209, v206, v104
	v_perm_b32 v81, v209, v206, v105
	v_perm_b32 v82, v213, v210, v104
	v_perm_b32 v83, v213, v210, v105
	s_mov_b64 s[70:71], s[90:91]
	s_mov_b32 s13, 0
	s_cmp_ge_u32 s52, s9
	s_cbranch_scc1 .Ldt0_nl3
	s_cmpk_ge_u32 s52, 0x1410
	s_cbranch_scc1 .Ldt0_out7
	s_sub_i32 s0, s52, 0xa08
	s_mul_i32 s1, s0, 0xcc3
	s_lshr_b32 s1, s1, 20
	s_mul_i32 s2, s1, 0x141
	s_sub_u32 s2, s0, s2
	s_lshl_b32 s3, s2, 7
	s_mul_i32 s4, s1, 0x1410000
	s_add_u32 s3, s3, s4
	s_add_u32 s64, s54, s3
	s_addc_u32 s65, s55, 0
	s_mov_b32 s7, 0xa080
	s_lshl_b32 s4, s1, 10
	s_cmpk_lt_u32 s2, 0x80
	s_cbranch_scc1 .Ldt0_wlo7
	s_cmpk_eq_u32 s2, 0x80
	s_cbranch_scc1 .Ldt0_wlr7
	s_add_i32 s2, s2, -1
